# k62: k58 + nt on the attention unit's output (O) stores
# speedup vs baseline: 1.0174x; 1.0122x over previous
; #define LAS __attribute__((address_space(3)))
; __device__ __forceinline__ int crow(int r, int hi) { return (r & 3) + 8 * (r >> 2) + 4 * hi; }
; __device__ __forceinline__ void attn_unit(const UnitDesc& u, LAS unsigned char* shm, float qkmax, float thresh) {
;     ...
;         { auto rr = __builtin_amdgcn_permlane32_swap(__float_as_uint(l_reg), __float_as_uint(l_reg), false, false); l_reg = __uint_as_float(rr[0]) + __uint_as_float(rr[1]); }
;         LAS float* lx = (LAS float*)(shm + LDS_LX) + wid * 32;
;         if (hi == 0) lx[r32] = l_reg;
;         asm volatile("s_waitcnt lgkmcnt(0)" ::: "memory");
;         float rli[16];
; #pragma unroll
;         for (int r = 0; r < 16; ++r) rli[r] = 1.f / lx[crow(r, hi)];
.LBB0_718:
	s_or_b64 exec, exec, s[8:9]
	s_waitcnt lgkmcnt(0)
	v_lshl_add_u32 v21, v142, 2, s10
	ds_read_b128 v[22:25], v21 offset:36864
	ds_read_b128 v[26:29], v21 offset:36896
	s_lshl_b64 s[8:9], s[34:35], 11
	s_add_u32 s8, s92, s8
	s_addc_u32 s10, s93, s9
	s_add_u32 s6, s8, s6
	s_waitcnt lgkmcnt(1)
	v_div_scale_f32 v30, s[8:9], v22, v22, 1.0
	v_rcp_f32_e32 v31, v30
	s_addc_u32 s7, s10, s7
	s_add_u32 s6, s6, 0x1800400
	s_addc_u32 s7, s7, 0
	v_fma_f32 v32, -v30, v31, 1.0
	v_fmac_f32_e32 v31, v32, v31
	v_div_scale_f32 v32, vcc, 1.0, v22, 1.0
	v_mul_f32_e32 v33, v32, v31
	v_fma_f32 v240, -v30, v33, v32
	v_fmac_f32_e32 v33, v240, v31
	v_fma_f32 v30, -v30, v33, v32
	v_div_scale_f32 v32, s[8:9], v23, v23, 1.0
	v_rcp_f32_e32 v240, v32
	v_div_fmas_f32 v30, v30, v31, v33
	v_div_fixup_f32 v241, v30, v22, 1.0
	v_mul_f32_e32 v34, v34, v241
	v_fma_f32 v22, -v32, v240, 1.0
	v_fmac_f32_e32 v240, v22, v240
	v_div_scale_f32 v22, vcc, 1.0, v23, 1.0
	v_mul_f32_e32 v30, v22, v240
	v_fma_f32 v31, -v32, v30, v22
	v_fmac_f32_e32 v30, v31, v240
	v_div_scale_f32 v31, s[8:9], v24, v24, 1.0
	v_fma_f32 v22, -v32, v30, v22
	v_rcp_f32_e32 v32, v31
	v_div_fmas_f32 v22, v22, v240, v30
	v_div_fixup_f32 v240, v22, v23, 1.0
	v_lshlrev_b64 v[18:19], 11, v[18:19]
	v_fma_f32 v22, -v31, v32, 1.0
	v_fmac_f32_e32 v32, v22, v32
	v_div_scale_f32 v22, vcc, 1.0, v24, 1.0
	v_mul_f32_e32 v23, v22, v32
	v_fma_f32 v30, -v31, v23, v22
	v_fmac_f32_e32 v23, v30, v32
	v_div_scale_f32 v30, s[8:9], v25, v25, 1.0
	v_fma_f32 v22, -v31, v23, v22
	v_rcp_f32_e32 v31, v30
	v_div_fmas_f32 v22, v22, v32, v23
	v_div_fixup_f32 v242, v22, v24, 1.0
	v_lshl_add_u64 v[18:19], s[6:7], 0, v[18:19]
	v_fma_f32 v22, -v30, v31, 1.0
	v_fmac_f32_e32 v31, v22, v31
	v_div_scale_f32 v22, vcc, 1.0, v25, 1.0
	v_mul_f32_e32 v23, v22, v31
	v_fma_f32 v24, -v30, v23, v22
	v_fmac_f32_e32 v23, v24, v31
	s_waitcnt lgkmcnt(0)
	v_div_scale_f32 v24, s[8:9], v26, v26, 1.0
	v_fma_f32 v22, -v30, v23, v22
	v_rcp_f32_e32 v30, v24
	v_div_fmas_f32 v22, v22, v31, v23
	v_div_fixup_f32 v243, v22, v25, 1.0
	v_div_scale_f32 v31, s[8:9], v29, v29, 1.0
	v_fma_f32 v22, -v24, v30, 1.0
	v_fmac_f32_e32 v30, v22, v30
	v_div_scale_f32 v22, vcc, 1.0, v26, 1.0
	v_mul_f32_e32 v23, v22, v30
	v_fma_f32 v25, -v24, v23, v22
	v_fmac_f32_e32 v23, v25, v30
	v_fma_f32 v22, -v24, v23, v22
	v_div_scale_f32 v24, s[8:9], v27, v27, 1.0
	v_rcp_f32_e32 v25, v24
	v_div_fmas_f32 v22, v22, v30, v23
	v_div_fixup_f32 v26, v22, v26, 1.0
	v_rcp_f32_e32 v244, v31
	v_fma_f32 v22, -v24, v25, 1.0
	v_fmac_f32_e32 v25, v22, v25
	v_div_scale_f32 v22, vcc, 1.0, v27, 1.0
	v_mul_f32_e32 v23, v22, v25
	v_fma_f32 v30, -v24, v23, v22
	v_fmac_f32_e32 v23, v30, v25
	v_fma_f32 v22, -v24, v23, v22
	v_div_scale_f32 v24, s[8:9], v28, v28, 1.0
	v_rcp_f32_e32 v30, v24
	v_div_fmas_f32 v22, v22, v25, v23
	v_div_fixup_f32 v27, v22, v27, 1.0
	v_lshl_add_u64 v[18:19], v[18:19], 0, v[0:1]
	v_fma_f32 v22, -v24, v30, 1.0
	v_fmac_f32_e32 v30, v22, v30
	v_div_scale_f32 v22, vcc, 1.0, v28, 1.0
	v_mul_f32_e32 v23, v22, v30
	v_fma_f32 v25, -v24, v23, v22
	v_fmac_f32_e32 v23, v25, v30
	v_fma_f32 v22, -v24, v23, v22
	v_div_fmas_f32 v22, v22, v30, v23
	v_div_fixup_f32 v28, v22, v28, 1.0
	v_fma_f32 v22, -v31, v244, 1.0
	v_fmac_f32_e32 v244, v22, v244
	ds_read_b128 v[22:25], v21 offset:36928
	v_div_scale_f32 v30, vcc, 1.0, v29, 1.0
	v_mul_f32_e32 v245, v30, v244
	v_fma_f32 v32, -v31, v245, v30
	v_fmac_f32_e32 v245, v32, v244
	v_fma_f32 v246, -v31, v245, v30
	ds_read_b128 v[30:33], v21 offset:36960
	s_waitcnt lgkmcnt(1)
	v_div_scale_f32 v21, s[8:9], v22, v22, 1.0
	v_rcp_f32_e32 v247, v21
	v_div_fmas_f32 v244, v246, v244, v245
	v_div_fixup_f32 v29, v244, v29, 1.0
	v_fma_f32 v244, -v21, v247, 1.0
	v_fmac_f32_e32 v247, v244, v247
	v_div_scale_f32 v244, vcc, 1.0, v22, 1.0
	v_mul_f32_e32 v245, v244, v247
	v_fma_f32 v246, -v21, v245, v244
	v_fmac_f32_e32 v245, v246, v247
	v_fma_f32 v21, -v21, v245, v244
	v_div_scale_f32 v244, s[8:9], v23, v23, 1.0
	v_rcp_f32_e32 v246, v244
	v_div_fmas_f32 v21, v21, v247, v245
	v_div_fixup_f32 v21, v21, v22, 1.0
	v_fma_f32 v22, -v244, v246, 1.0
	v_fmac_f32_e32 v246, v22, v246
	v_div_scale_f32 v22, vcc, 1.0, v23, 1.0
	v_mul_f32_e32 v245, v22, v246
	v_fma_f32 v247, -v244, v245, v22
	v_fmac_f32_e32 v245, v247, v246
	v_fma_f32 v22, -v244, v245, v22
	v_div_scale_f32 v244, s[8:9], v24, v24, 1.0
	v_rcp_f32_e32 v247, v244
	v_div_fmas_f32 v22, v22, v246, v245
	v_div_fixup_f32 v22, v22, v23, 1.0
	v_fma_f32 v23, -v244, v247, 1.0
	v_fmac_f32_e32 v247, v23, v247
	v_div_scale_f32 v23, vcc, 1.0, v24, 1.0
	v_mul_f32_e32 v245, v23, v247
	v_fma_f32 v246, -v244, v245, v23
	v_fmac_f32_e32 v245, v246, v247
	v_fma_f32 v23, -v244, v245, v23
	v_div_scale_f32 v244, s[8:9], v25, v25, 1.0
	v_rcp_f32_e32 v246, v244
	v_div_fmas_f32 v23, v23, v247, v245
	v_div_fixup_f32 v23, v23, v24, 1.0
	v_fma_f32 v24, -v244, v246, 1.0
	v_fmac_f32_e32 v246, v24, v246
	v_div_scale_f32 v24, vcc, 1.0, v25, 1.0
	v_mul_f32_e32 v245, v24, v246
	v_fma_f32 v247, -v244, v245, v24
	v_fmac_f32_e32 v245, v247, v246
	v_fma_f32 v24, -v244, v245, v24
	s_waitcnt lgkmcnt(0)
; #define LAS __attribute__((address_space(3)))
; __device__ __forceinline__ unsigned f2bf(float f) { unsigned u = __builtin_bit_cast(unsigned, f); return (u + 0x7fffu + ((u >> 16) & 1u)) >> 16; }
; __device__ __forceinline__ int crow(int r, int hi) { return (r & 3) + 8 * (r >> 2) + 4 * hi; }
; __device__ __forceinline__ void attn_unit(const UnitDesc& u, LAS unsigned char* shm, float qkmax, float thresh) {
;     ...
;         float rli[16];
; #pragma unroll
;         for (int r = 0; r < 16; ++r) rli[r] = 1.f / lx[crow(r, hi)];
;         LAS bf16_t* stg = (LAS bf16_t*)(shm + LDS_OST) + wid * 2048;
; #pragma unroll
;         for (int r = 0; r < 16; ++r) { const int orow = crow(r, hi);
; #pragma unroll
;             for (int d0 = 0; d0 < 2; ++d0) stg[orow * 64 + d0 * 32 + r32] = (bf16_t)f2bf(o[d0][r] * rli[r]); }
	v_div_scale_f32 v244, s[8:9], v30, v30, 1.0
	v_rcp_f32_e32 v247, v244
	v_div_fmas_f32 v24, v24, v246, v245
	v_div_fixup_f32 v24, v24, v25, 1.0
	v_fma_f32 v25, -v244, v247, 1.0
	v_fmac_f32_e32 v247, v25, v247
	v_div_scale_f32 v25, vcc, 1.0, v30, 1.0
	v_mul_f32_e32 v245, v25, v247
	v_fma_f32 v246, -v244, v245, v25
	v_fmac_f32_e32 v245, v246, v247
	v_fma_f32 v25, -v244, v245, v25
	v_div_scale_f32 v244, s[8:9], v31, v31, 1.0
	v_rcp_f32_e32 v246, v244
	v_div_fmas_f32 v25, v25, v247, v245
	v_div_fixup_f32 v25, v25, v30, 1.0
	v_fma_f32 v30, -v244, v246, 1.0
	v_fmac_f32_e32 v246, v30, v246
	v_div_scale_f32 v30, vcc, 1.0, v31, 1.0
	v_mul_f32_e32 v245, v30, v246
	v_fma_f32 v247, -v244, v245, v30
	v_fmac_f32_e32 v245, v247, v246
	v_fma_f32 v30, -v244, v245, v30
	v_div_scale_f32 v244, s[8:9], v32, v32, 1.0
	v_rcp_f32_e32 v247, v244
	v_div_fmas_f32 v30, v30, v246, v245
	v_div_fixup_f32 v30, v30, v31, 1.0
	v_fma_f32 v31, -v244, v247, 1.0
	v_fmac_f32_e32 v247, v31, v247
	v_div_scale_f32 v31, vcc, 1.0, v32, 1.0
	v_mul_f32_e32 v245, v31, v247
	v_fma_f32 v246, -v244, v245, v31
	v_fmac_f32_e32 v245, v246, v247
	v_fma_f32 v31, -v244, v245, v31
	v_div_scale_f32 v244, s[8:9], v33, v33, 1.0
	v_rcp_f32_e32 v246, v244
	v_div_fmas_f32 v31, v31, v247, v245
	v_div_fixup_f32 v31, v31, v32, 1.0
	s_lshl_b32 s8, s52, 12
	v_fma_f32 v32, -v244, v246, 1.0
	v_fmac_f32_e32 v246, v32, v246
	v_div_scale_f32 v32, vcc, 1.0, v33, 1.0
	v_mul_f32_e32 v245, v32, v246
	v_fma_f32 v247, -v244, v245, v32
	v_fmac_f32_e32 v245, v247, v246
	v_fma_f32 v32, -v244, v245, v32
	v_div_fmas_f32 v32, v32, v246, v245
	v_div_fixup_f32 v32, v32, v33, 1.0
	s_add_i32 s8, s8, 0
	v_lshlrev_b32_e32 v33, 1, v135
	v_lshlrev_b32_e32 v244, 9, v136
	v_add3_u32 v33, s8, v33, v244
	v_bfe_u32 v244, v34, 16, 1
	v_add3_u32 v34, v34, v244, s51
	ds_write_b16_d16_hi v33, v34 offset:37888
	v_mul_f32_e32 v34, v50, v241
	v_bfe_u32 v50, v34, 16, 1
	v_add3_u32 v34, v34, v50, s51
	ds_write_b16_d16_hi v33, v34 offset:37952
	v_mul_f32_e32 v34, v35, v240
	v_bfe_u32 v35, v34, 16, 1
	v_add3_u32 v34, v34, v35, s51
	ds_write_b16_d16_hi v33, v34 offset:38016
	v_mul_f32_e32 v34, v51, v240
	v_bfe_u32 v35, v34, 16, 1
	v_add3_u32 v34, v34, v35, s51
	ds_write_b16_d16_hi v33, v34 offset:38080
	v_mul_f32_e32 v34, v36, v242
	v_bfe_u32 v35, v34, 16, 1
	v_add3_u32 v34, v34, v35, s51
	ds_write_b16_d16_hi v33, v34 offset:38144
	v_mul_f32_e32 v34, v52, v242
	v_bfe_u32 v35, v34, 16, 1
	v_add3_u32 v34, v34, v35, s51
	ds_write_b16_d16_hi v33, v34 offset:38208
	v_mul_f32_e32 v34, v37, v243
	v_bfe_u32 v35, v34, 16, 1
	v_add3_u32 v34, v34, v35, s51
	ds_write_b16_d16_hi v33, v34 offset:38272
	v_mul_f32_e32 v34, v53, v243
	v_bfe_u32 v35, v34, 16, 1
	v_add3_u32 v34, v34, v35, s51
	ds_write_b16_d16_hi v33, v34 offset:38336
	v_mul_f32_e32 v34, v38, v26
	v_bfe_u32 v35, v34, 16, 1
	v_add3_u32 v34, v34, v35, s51
	v_mul_f32_e32 v26, v54, v26
	ds_write_b16_d16_hi v33, v34 offset:38912
	v_bfe_u32 v34, v26, 16, 1
	v_add3_u32 v26, v26, v34, s51
	ds_write_b16_d16_hi v33, v26 offset:38976
	v_mul_f32_e32 v26, v39, v27
	v_bfe_u32 v34, v26, 16, 1
	v_add3_u32 v26, v26, v34, s51
	ds_write_b16_d16_hi v33, v26 offset:39040
	v_mul_f32_e32 v26, v55, v27
	v_bfe_u32 v27, v26, 16, 1
	v_add3_u32 v26, v26, v27, s51
	ds_write_b16_d16_hi v33, v26 offset:39104
	v_mul_f32_e32 v26, v40, v28
	v_bfe_u32 v27, v26, 16, 1
	v_add3_u32 v26, v26, v27, s51
	ds_write_b16_d16_hi v33, v26 offset:39168
	v_mul_f32_e32 v26, v56, v28
	v_bfe_u32 v27, v26, 16, 1
	v_add3_u32 v26, v26, v27, s51
	ds_write_b16_d16_hi v33, v26 offset:39232
	v_mul_f32_e32 v26, v41, v29
	v_bfe_u32 v27, v26, 16, 1
	v_add3_u32 v26, v26, v27, s51
	ds_write_b16_d16_hi v33, v26 offset:39296
	v_mul_f32_e32 v26, v57, v29
	v_bfe_u32 v27, v26, 16, 1
	v_add3_u32 v26, v26, v27, s51
	ds_write_b16_d16_hi v33, v26 offset:39360
	v_mul_f32_e32 v26, v42, v21
	v_bfe_u32 v27, v26, 16, 1
	v_add3_u32 v26, v26, v27, s51
	v_mul_f32_e32 v21, v58, v21
	ds_write_b16_d16_hi v33, v26 offset:39936
	v_bfe_u32 v26, v21, 16, 1
	v_add3_u32 v21, v21, v26, s51
	ds_write_b16_d16_hi v33, v21 offset:40000
	v_mul_f32_e32 v21, v43, v22
	v_bfe_u32 v26, v21, 16, 1
	v_add3_u32 v21, v21, v26, s51
	ds_write_b16_d16_hi v33, v21 offset:40064
	v_mul_f32_e32 v21, v59, v22
	v_bfe_u32 v22, v21, 16, 1
	v_add3_u32 v21, v21, v22, s51
	ds_write_b16_d16_hi v33, v21 offset:40128
	v_mul_f32_e32 v21, v44, v23
	v_bfe_u32 v22, v21, 16, 1
	v_add3_u32 v21, v21, v22, s51
	ds_write_b16_d16_hi v33, v21 offset:40192
	v_mul_f32_e32 v21, v60, v23
	v_bfe_u32 v22, v21, 16, 1
	v_add3_u32 v21, v21, v22, s51
	ds_write_b16_d16_hi v33, v21 offset:40256
	v_mul_f32_e32 v21, v45, v24
	v_bfe_u32 v22, v21, 16, 1
	v_add3_u32 v21, v21, v22, s51
	ds_write_b16_d16_hi v33, v21 offset:40320
	v_mul_f32_e32 v21, v61, v24
	v_bfe_u32 v22, v21, 16, 1
	v_add3_u32 v21, v21, v22, s51
	ds_write_b16_d16_hi v33, v21 offset:40384
	v_mul_f32_e32 v21, v46, v25
	v_bfe_u32 v22, v21, 16, 1
	v_add3_u32 v21, v21, v22, s51
	ds_write_b16_d16_hi v33, v21 offset:40960
	v_mul_f32_e32 v21, v62, v25
	v_bfe_u32 v22, v21, 16, 1
	v_add3_u32 v21, v21, v22, s51
	ds_write_b16_d16_hi v33, v21 offset:41024
	v_mul_f32_e32 v21, v47, v30
	v_bfe_u32 v22, v21, 16, 1
	v_add3_u32 v21, v21, v22, s51
	ds_write_b16_d16_hi v33, v21 offset:41088
	v_mul_f32_e32 v21, v63, v30
	v_bfe_u32 v22, v21, 16, 1
	v_add3_u32 v21, v21, v22, s51
	ds_write_b16_d16_hi v33, v21 offset:41152
	v_mul_f32_e32 v21, v48, v31
	v_bfe_u32 v22, v21, 16, 1
	v_add3_u32 v21, v21, v22, s51
	ds_write_b16_d16_hi v33, v21 offset:41216
	v_mul_f32_e32 v21, v64, v31
	v_bfe_u32 v22, v21, 16, 1
	v_add3_u32 v21, v21, v22, s51
	ds_write_b16_d16_hi v33, v21 offset:41280
	v_mul_f32_e32 v21, v49, v32
	v_bfe_u32 v22, v21, 16, 1
	v_add3_u32 v21, v21, v22, s51
	ds_write_b16_d16_hi v33, v21 offset:41344
	v_mul_f32_e32 v21, v65, v32
	v_bfe_u32 v22, v21, 16, 1
	v_add3_u32 v21, v21, v22, s51
	ds_write_b16_d16_hi v33, v21 offset:41408
	v_add_u32_e32 v21, s8, v0
	s_waitcnt lgkmcnt(0)
; #define LAS __attribute__((address_space(3)))
; __device__ __forceinline__ unsigned pk2(float lo, float hi) { typedef __bf16 bf16x2_t_ __attribute__((ext_vector_type(2))); f32x2 v = {lo, hi}; return __builtin_bit_cast(unsigned, __builtin_convertvector(v, bf16x2_t_)); }
; __device__ __forceinline__ void attn_unit(const UnitDesc& u, LAS unsigned char* shm, float qkmax, float thresh) {
;     ...
;         asm volatile("s_waitcnt lgkmcnt(0)" ::: "memory");
; #pragma unroll
;         for (int i = 0; i < 4; ++i) { const int row = i * 8 + (lane >> 3), ch = lane & 7;
;             const u32x4 ov = *(const LAS u32x4*)(stg + row * 64 + ch * 8);
;             const u32x4 zv = zv4[i];
;             u32x4 w; w.x = pk2(bflo(ov.x) * bflo(zv.x), bfhi(ov.x) * bfhi(zv.x)); w.y = pk2(bflo(ov.y) * bflo(zv.y), bfhi(ov.y) * bfhi(zv.y));
;             w.z = pk2(bflo(ov.z) * bflo(zv.z), bfhi(ov.z) * bfhi(zv.z)); w.w = pk2(bflo(ov.w) * bflo(zv.w), bfhi(ov.w) * bfhi(zv.w));
;             *(u32x4*)(u.O + (size_t)(wid * 32 + row) * 1024 + ch * 8) = w; }
	v_lshl_add_u32 v22, v20, 7, v21
	ds_read_b128 v[22:25], v22 offset:37888
	v_or_b32_e32 v34, 8, v20
	v_lshl_add_u32 v26, v34, 7, v21
	ds_read_b128 v[26:29], v26 offset:37888
	s_waitcnt vmcnt(3)
	v_lshlrev_b32_e32 v32, 16, v14
	s_waitcnt lgkmcnt(1)
	v_lshlrev_b32_e32 v30, 16, v22
	v_and_b32_e32 v31, 0xffff0000, v22
	v_and_b32_e32 v33, 0xffff0000, v14
	v_pk_mul_f32 v[30:31], v[32:33], v[30:31]
	v_lshlrev_b32_e32 v22, 16, v23
	v_cvt_pk_bf16_f32 v14, v30, v31
	v_and_b32_e32 v23, 0xffff0000, v23
	v_lshlrev_b32_e32 v30, 16, v15
	v_and_b32_e32 v31, 0xffff0000, v15
	v_pk_mul_f32 v[22:23], v[30:31], v[22:23]
	v_lshlrev_b32_e32 v30, 16, v16
	v_cvt_pk_bf16_f32 v15, v22, v23
	v_lshlrev_b32_e32 v22, 16, v24
	v_and_b32_e32 v23, 0xffff0000, v24
	v_and_b32_e32 v31, 0xffff0000, v16
	v_pk_mul_f32 v[22:23], v[30:31], v[22:23]
	v_lshlrev_b32_e32 v24, 16, v17
	v_cvt_pk_bf16_f32 v16, v22, v23
	v_lshlrev_b32_e32 v22, 16, v25
	v_and_b32_e32 v23, 0xffff0000, v25
	v_and_b32_e32 v25, 0xffff0000, v17
	v_pk_mul_f32 v[22:23], v[24:25], v[22:23]
	s_nop 0
	v_cvt_pk_bf16_f32 v17, v22, v23
	global_store_dwordx4 v[18:19], v[14:17], off nt
	v_or_b32_e32 v22, 16, v20
	v_or_b32_e32 v23, 24, v20
	s_waitcnt lgkmcnt(0)
	v_lshlrev_b32_e32 v14, 16, v26
	v_and_b32_e32 v15, 0xffff0000, v26
	s_waitcnt vmcnt(3)
	v_lshlrev_b32_e32 v16, 16, v10
	v_and_b32_e32 v17, 0xffff0000, v10
	v_pk_mul_f32 v[14:15], v[16:17], v[14:15]
	v_lshlrev_b32_e32 v16, 16, v11
	v_cvt_pk_bf16_f32 v10, v14, v15
	v_lshlrev_b32_e32 v14, 16, v27
	v_and_b32_e32 v15, 0xffff0000, v27
	v_and_b32_e32 v17, 0xffff0000, v11
	v_pk_mul_f32 v[14:15], v[16:17], v[14:15]
	v_lshlrev_b32_e32 v16, 16, v12
	v_cvt_pk_bf16_f32 v11, v14, v15
	v_lshlrev_b32_e32 v14, 16, v28
	v_and_b32_e32 v15, 0xffff0000, v28
	v_and_b32_e32 v17, 0xffff0000, v12
	v_pk_mul_f32 v[14:15], v[16:17], v[14:15]
	v_lshlrev_b32_e32 v16, 16, v13
	v_cvt_pk_bf16_f32 v12, v14, v15
	v_lshlrev_b32_e32 v14, 16, v29
	v_and_b32_e32 v15, 0xffff0000, v29
	v_and_b32_e32 v17, 0xffff0000, v13
	v_pk_mul_f32 v[14:15], v[16:17], v[14:15]
	s_waitcnt vmcnt(2)
	v_lshlrev_b32_e32 v20, 16, v6
	v_cvt_pk_bf16_f32 v13, v14, v15
	v_or_b32_e32 v14, s49, v34
	v_ashrrev_i32_e32 v15, 31, v14
	v_lshlrev_b64 v[14:15], 11, v[14:15]
	v_lshl_add_u64 v[14:15], s[6:7], 0, v[14:15]
	v_lshl_add_u64 v[18:19], v[14:15], 0, v[0:1]
	v_lshl_add_u32 v14, v22, 7, v21
	ds_read_b128 v[14:17], v14 offset:37888
	global_store_dwordx4 v[18:19], v[10:13], off nt
	s_nop 1
	v_lshl_add_u32 v10, v23, 7, v21
	ds_read_b128 v[10:13], v10 offset:37888
	s_waitcnt lgkmcnt(1)
	v_lshlrev_b32_e32 v18, 16, v14
	v_and_b32_e32 v19, 0xffff0000, v14
	v_and_b32_e32 v21, 0xffff0000, v6
	v_pk_mul_f32 v[18:19], v[20:21], v[18:19]
	v_lshlrev_b32_e32 v14, 16, v15
	v_cvt_pk_bf16_f32 v6, v18, v19
	v_and_b32_e32 v15, 0xffff0000, v15
	v_lshlrev_b32_e32 v18, 16, v7
	v_and_b32_e32 v19, 0xffff0000, v7
	v_pk_mul_f32 v[14:15], v[18:19], v[14:15]
	v_lshlrev_b32_e32 v18, 16, v8
	v_cvt_pk_bf16_f32 v7, v14, v15
	v_lshlrev_b32_e32 v14, 16, v16
	v_and_b32_e32 v15, 0xffff0000, v16
	v_and_b32_e32 v19, 0xffff0000, v8
	v_pk_mul_f32 v[14:15], v[18:19], v[14:15]
	v_lshlrev_b32_e32 v16, 16, v9
	v_cvt_pk_bf16_f32 v8, v14, v15
	v_lshlrev_b32_e32 v14, 16, v17
	v_and_b32_e32 v15, 0xffff0000, v17
	v_and_b32_e32 v17, 0xffff0000, v9
	v_pk_mul_f32 v[14:15], v[16:17], v[14:15]
	s_nop 0
	v_cvt_pk_bf16_f32 v9, v14, v15
	v_or_b32_e32 v14, s49, v22
	v_ashrrev_i32_e32 v15, 31, v14
	v_lshlrev_b64 v[14:15], 11, v[14:15]
	v_lshl_add_u64 v[14:15], s[6:7], 0, v[14:15]
	v_lshl_add_u64 v[14:15], v[14:15], 0, v[0:1]
	global_store_dwordx4 v[14:15], v[6:9], off nt
	s_waitcnt lgkmcnt(0)
	s_nop 0
	v_lshlrev_b32_e32 v6, 16, v10
	v_and_b32_e32 v7, 0xffff0000, v10
	s_waitcnt vmcnt(3)
	v_lshlrev_b32_e32 v8, 16, v2
	v_and_b32_e32 v9, 0xffff0000, v2
	v_pk_mul_f32 v[6:7], v[8:9], v[6:7]
	v_lshlrev_b32_e32 v8, 16, v3
	v_cvt_pk_bf16_f32 v2, v6, v7
	v_lshlrev_b32_e32 v6, 16, v11
	v_and_b32_e32 v7, 0xffff0000, v11
	v_and_b32_e32 v9, 0xffff0000, v3
	v_pk_mul_f32 v[6:7], v[8:9], v[6:7]
	v_lshlrev_b32_e32 v8, 16, v4
	v_cvt_pk_bf16_f32 v3, v6, v7
	v_lshlrev_b32_e32 v6, 16, v12
	v_and_b32_e32 v7, 0xffff0000, v12
	v_and_b32_e32 v9, 0xffff0000, v4
	v_pk_mul_f32 v[6:7], v[8:9], v[6:7]
	v_lshlrev_b32_e32 v8, 16, v5
	v_cvt_pk_bf16_f32 v4, v6, v7
	v_lshlrev_b32_e32 v6, 16, v13
	v_and_b32_e32 v7, 0xffff0000, v13
	v_and_b32_e32 v9, 0xffff0000, v5
	v_pk_mul_f32 v[6:7], v[8:9], v[6:7]
	s_nop 0
	v_cvt_pk_bf16_f32 v5, v6, v7
	v_or_b32_e32 v6, s49, v23
	v_ashrrev_i32_e32 v7, 31, v6
	v_lshlrev_b64 v[6:7], 11, v[6:7]
	v_lshl_add_u64 v[6:7], s[6:7], 0, v[6:7]
	v_lshl_add_u64 v[6:7], v[6:7], 0, v[0:1]
	global_store_dwordx4 v[6:7], v[2:5], off nt
